# FF1 K-loop: the two LDS-DMA loads of each phase are issued inside that phase's MFMA block (between MFMAs) instead of in the load segment; vmcnt(6)->vmcnt(4)
# speedup vs baseline: 1.0051x; 1.0020x over previous
; #define PG8_STAGE(bufoff, gbase, voff) do { _Pragma("unroll") for (int _i = 0; _i < 2; ++_i) \
;         __builtin_amdgcn_global_load_lds((const unsigned*)((const char*)(gbase) + (voff)[_i]), (LAS unsigned*)(lds + (bufoff) + ldsw + _i * 8192), 16, 0, 0); } while (0)
; #define PG8_LDA(dst, b, h) do { _Pragma("unroll") for (int m = 0; m < 4; ++m) _Pragma("unroll") for (int k = 0; k < 2; ++k) dst[m][k] = *(const LAS bf16x8*)(lds + PG8_SA(b, h) + aoff + m * 2048 + k * 1024); } while (0)
; #define PG8_LDB(dst, b, h) do { _Pragma("unroll") for (int n = 0; n < 2; ++n) _Pragma("unroll") for (int k = 0; k < 2; ++k) dst[n][k] = *(const LAS bf16x8*)(lds + PG8_SB(b, h) + boff + n * 2048 + k * 1024); } while (0)
; #define PG8_MMA(ai, bj, At, Bt) do { __builtin_amdgcn_s_setprio(1); _Pragma("unroll") for (int m = 0; m < 4; ++m) _Pragma("unroll") for (int n = 0; n < 2; ++n) _Pragma("unroll") for (int k = 0; k < 2; ++k) \
;         acc[ai][bj][m][n] = __builtin_amdgcn_mfma_f32_16x16x32_bf16(Bt[n][k], At[m][k], acc[ai][bj][m][n], 0, 0, 0); __builtin_amdgcn_s_setprio(0); } while (0)
; #define PG8_WAIT_V(n) asm volatile("s_waitcnt vmcnt(" #n ")" ::: "memory")
; #define PG8_WAIT_L(n) asm volatile("s_waitcnt lgkmcnt(" #n ")" ::: "memory")
; #define PG8_BAR __builtin_amdgcn_s_barrier()
; #define PG8_SCHED __builtin_amdgcn_sched_barrier(0)
; template <class Epi, class Sched>
; __device__ __forceinline__ void gemm_phase(LAS unsigned char* lds, const Gemm g, const Sched& S, const Epi& E) {
;     ...
;             PG8_LDB(B0, 0, 0); PG8_SCHED; PG8_LDA(At, 0, 0); PG8_STAGE(PG8_SA(1, 1), a1 + hstep, voffA);
;             PG8_WAIT_L(8); PG8_BAR; PG8_WAIT_L(0); PG8_MMA(0, 0, At, B0); PG8_BAR; PG8_SCHED;
;             PG8_LDB(B1, 0, 1); PG8_STAGE(PG8_SB(0, 0), b2, voffB);
;             PG8_BAR; PG8_WAIT_L(0); PG8_MMA(0, 1, At, B1); PG8_BAR;
;             PG8_LDA(At, 0, 1); PG8_STAGE(PG8_SA(0, 0), a2, voffA);
;             PG8_BAR; PG8_WAIT_L(0); PG8_MMA(1, 0, At, B0); PG8_BAR; PG8_SCHED;
;             PG8_STAGE(PG8_SB(0, 1), b2 + hstep, voffB);
;             PG8_WAIT_V(6); PG8_BAR; PG8_MMA(1, 1, At, B1); PG8_BAR;
.LBB0_1279:
	s_nop 0
	v_add_u32_e32 v140, s47, v143
	ds_read_b128 v[146:149], v140
	ds_read_b128 v[150:153], v140 offset:1024
	ds_read_b128 v[154:157], v140 offset:2048
	ds_read_b128 v[158:161], v140 offset:3072
	s_add_u32 s22, s20, 0xfff80080
	s_addc_u32 s23, s21, -1
	s_cmp_eq_u32 s43, 28
	s_cselect_b32 s25, s3, s23
	s_cselect_b32 s24, s11, s22
	s_cselect_b32 s23, s9, s42
	s_cselect_b32 s22, s40, s41
	ds_read_b128 v[162:165], v145
	ds_read_b128 v[166:169], v145 offset:1024
	ds_read_b128 v[170:173], v145 offset:2048
	ds_read_b128 v[174:177], v145 offset:3072
	ds_read_b128 v[178:181], v145 offset:4096
	ds_read_b128 v[182:185], v145 offset:5120
	ds_read_b128 v[186:189], v145 offset:6144
	ds_read_b128 v[190:193], v145 offset:7168
	s_waitcnt lgkmcnt(8)
	s_barrier
	s_waitcnt lgkmcnt(0)
	v_mfma_f32_16x16x32_bf16 v[126:129], v[146:149], v[162:165], v[126:129]
	v_mfma_f32_16x16x32_bf16 v[122:125], v[154:157], v[162:165], v[122:125]
	v_mfma_f32_16x16x32_bf16 v[110:113], v[146:149], v[170:173], v[110:113]
	v_mfma_f32_16x16x32_bf16 v[106:109], v[154:157], v[170:173], v[106:109]
	s_add_i32 m0, s17, 0xc000
	v_mfma_f32_16x16x32_bf16 v[94:97], v[146:149], v[178:181], v[94:97]
	global_load_lds_dwordx4 v136, s[20:21]
	v_mfma_f32_16x16x32_bf16 v[90:93], v[154:157], v[178:181], v[90:93]
	v_mfma_f32_16x16x32_bf16 v[78:81], v[146:149], v[186:189], v[78:81]
	v_mfma_f32_16x16x32_bf16 v[74:77], v[154:157], v[186:189], v[74:77]
	v_mfma_f32_16x16x32_bf16 v[126:129], v[150:153], v[166:169], v[126:129]
	v_mfma_f32_16x16x32_bf16 v[122:125], v[158:161], v[166:169], v[122:125]
	s_add_i32 m0, s17, 0xe000
	v_mfma_f32_16x16x32_bf16 v[110:113], v[150:153], v[174:177], v[110:113]
	global_load_lds_dwordx4 v138, s[20:21]
	v_mfma_f32_16x16x32_bf16 v[106:109], v[158:161], v[174:177], v[106:109]
	v_mfma_f32_16x16x32_bf16 v[94:97], v[150:153], v[182:185], v[94:97]
	v_mfma_f32_16x16x32_bf16 v[90:93], v[158:161], v[182:185], v[90:93]
	v_mfma_f32_16x16x32_bf16 v[78:81], v[150:153], v[190:193], v[78:81]
	v_mfma_f32_16x16x32_bf16 v[74:77], v[158:161], v[190:193], v[74:77]
	s_barrier
	s_add_i32 s46, 0, 0x14000
	v_add_u32_e32 v140, s46, v143
	s_add_i32 s44, s47, s30
	ds_read_b128 v[194:197], v140
	ds_read_b128 v[198:201], v140 offset:1024
	ds_read_b128 v[202:205], v140 offset:2048
	ds_read_b128 v[206:209], v140 offset:3072
	s_barrier
	s_waitcnt lgkmcnt(0)
	v_mfma_f32_16x16x32_bf16 v[118:121], v[194:197], v[162:165], v[118:121]
	v_mfma_f32_16x16x32_bf16 v[114:117], v[202:205], v[162:165], v[114:117]
	v_mfma_f32_16x16x32_bf16 v[102:105], v[194:197], v[170:173], v[102:105]
	v_mfma_f32_16x16x32_bf16 v[98:101], v[202:205], v[170:173], v[98:101]
	s_mov_b32 m0, s44
	v_mfma_f32_16x16x32_bf16 v[86:89], v[194:197], v[178:181], v[86:89]
	global_load_lds_dwordx4 v0, s[22:23]
	v_mfma_f32_16x16x32_bf16 v[82:85], v[202:205], v[178:181], v[82:85]
	v_mfma_f32_16x16x32_bf16 v[70:73], v[194:197], v[186:189], v[70:73]
	v_mfma_f32_16x16x32_bf16 v[66:69], v[202:205], v[186:189], v[66:69]
	v_mfma_f32_16x16x32_bf16 v[118:121], v[198:201], v[166:169], v[118:121]
	v_mfma_f32_16x16x32_bf16 v[114:117], v[206:209], v[166:169], v[114:117]
	s_add_i32 m0, s44, 0x2000
	v_mfma_f32_16x16x32_bf16 v[102:105], v[198:201], v[174:177], v[102:105]
	global_load_lds_dwordx4 v130, s[22:23]
	v_mfma_f32_16x16x32_bf16 v[98:101], v[206:209], v[174:177], v[98:101]
	v_mfma_f32_16x16x32_bf16 v[86:89], v[198:201], v[182:185], v[86:89]
	v_mfma_f32_16x16x32_bf16 v[82:85], v[206:209], v[182:185], v[82:85]
	v_mfma_f32_16x16x32_bf16 v[70:73], v[198:201], v[190:193], v[70:73]
	v_mfma_f32_16x16x32_bf16 v[66:69], v[206:209], v[190:193], v[66:69]
	s_add_u32 s48, s24, 0x80
	s_addc_u32 s49, s25, 0
	s_barrier
	ds_read_b128 v[162:165], v145 offset:16384
	ds_read_b128 v[166:169], v145 offset:17408
	ds_read_b128 v[170:173], v145 offset:18432
	ds_read_b128 v[174:177], v145 offset:19456
	ds_read_b128 v[178:181], v145 offset:20480
	ds_read_b128 v[182:185], v145 offset:21504
	ds_read_b128 v[186:189], v145 offset:22528
	ds_read_b128 v[190:193], v145 offset:23552
	s_barrier
	s_waitcnt lgkmcnt(0)
	v_mfma_f32_16x16x32_bf16 v[62:65], v[146:149], v[162:165], v[62:65]
	v_mfma_f32_16x16x32_bf16 v[58:61], v[154:157], v[162:165], v[58:61]
	v_mfma_f32_16x16x32_bf16 v[46:49], v[146:149], v[170:173], v[46:49]
	v_mfma_f32_16x16x32_bf16 v[42:45], v[154:157], v[170:173], v[42:45]
	s_mov_b32 m0, s17
	v_mfma_f32_16x16x32_bf16 v[30:33], v[146:149], v[178:181], v[30:33]
	global_load_lds_dwordx4 v134, s[24:25]
	v_mfma_f32_16x16x32_bf16 v[26:29], v[154:157], v[178:181], v[26:29]
	v_mfma_f32_16x16x32_bf16 v[14:17], v[146:149], v[186:189], v[14:17]
	v_mfma_f32_16x16x32_bf16 v[10:13], v[154:157], v[186:189], v[10:13]
	v_mfma_f32_16x16x32_bf16 v[62:65], v[150:153], v[166:169], v[62:65]
	v_mfma_f32_16x16x32_bf16 v[58:61], v[158:161], v[166:169], v[58:61]
	s_mov_b32 m0, s19
	v_mfma_f32_16x16x32_bf16 v[46:49], v[150:153], v[174:177], v[46:49]
	global_load_lds_dwordx4 v132, s[24:25]
	v_mfma_f32_16x16x32_bf16 v[42:45], v[158:161], v[174:177], v[42:45]
	v_mfma_f32_16x16x32_bf16 v[30:33], v[150:153], v[182:185], v[30:33]
	v_mfma_f32_16x16x32_bf16 v[26:29], v[158:161], v[182:185], v[26:29]
	v_mfma_f32_16x16x32_bf16 v[14:17], v[150:153], v[190:193], v[14:17]
	v_mfma_f32_16x16x32_bf16 v[10:13], v[158:161], v[190:193], v[10:13]
	s_barrier
	s_add_u32 s44, s22, 0x80000
	s_addc_u32 s45, s23, 0
	s_add_i32 s46, s46, s30
	s_waitcnt vmcnt(4)
	s_barrier
; #define PG8_STAGE(bufoff, gbase, voff) do { _Pragma("unroll") for (int _i = 0; _i < 2; ++_i) \
;         __builtin_amdgcn_global_load_lds((const unsigned*)((const char*)(gbase) + (voff)[_i]), (LAS unsigned*)(lds + (bufoff) + ldsw + _i * 8192), 16, 0, 0); } while (0)
; #define PG8_LDA(dst, b, h) do { _Pragma("unroll") for (int m = 0; m < 4; ++m) _Pragma("unroll") for (int k = 0; k < 2; ++k) dst[m][k] = *(const LAS bf16x8*)(lds + PG8_SA(b, h) + aoff + m * 2048 + k * 1024); } while (0)
; #define PG8_LDB(dst, b, h) do { _Pragma("unroll") for (int n = 0; n < 2; ++n) _Pragma("unroll") for (int k = 0; k < 2; ++k) dst[n][k] = *(const LAS bf16x8*)(lds + PG8_SB(b, h) + boff + n * 2048 + k * 1024); } while (0)
; #define PG8_MMA(ai, bj, At, Bt) do { __builtin_amdgcn_s_setprio(1); _Pragma("unroll") for (int m = 0; m < 4; ++m) _Pragma("unroll") for (int n = 0; n < 2; ++n) _Pragma("unroll") for (int k = 0; k < 2; ++k) \
;         acc[ai][bj][m][n] = __builtin_amdgcn_mfma_f32_16x16x32_bf16(Bt[n][k], At[m][k], acc[ai][bj][m][n], 0, 0, 0); __builtin_amdgcn_s_setprio(0); } while (0)
; #define PG8_WAIT_V(n) asm volatile("s_waitcnt vmcnt(" #n ")" ::: "memory")
; #define PG8_WAIT_L(n) asm volatile("s_waitcnt lgkmcnt(" #n ")" ::: "memory")
; #define PG8_BAR __builtin_amdgcn_s_barrier()
; #define PG8_SCHED __builtin_amdgcn_sched_barrier(0)
; template <class Epi, class Sched>
; __device__ __forceinline__ void gemm_phase(LAS unsigned char* lds, const Gemm g, const Sched& S, const Epi& E) {
;     ...
;             PG8_WAIT_V(6); PG8_BAR; PG8_MMA(1, 1, At, B1); PG8_BAR;
;             PG8_LDB(B0, 1, 0); PG8_SCHED; PG8_LDA(At, 1, 0); PG8_STAGE(PG8_SA(0, 1), a2 + hstep, voffA);
;             PG8_WAIT_L(8); PG8_BAR; PG8_WAIT_L(0); PG8_MMA(0, 0, At, B0); PG8_BAR; PG8_SCHED;
;             PG8_LDB(B1, 1, 1); PG8_STAGE(PG8_SB(1, 0), b3, voffB);
;             PG8_BAR; PG8_WAIT_L(0); PG8_MMA(0, 1, At, B1); PG8_BAR;
;             PG8_LDA(At, 1, 1); PG8_STAGE(PG8_SA(1, 0), a3, voffA);
	v_mfma_f32_16x16x32_bf16 v[54:57], v[194:197], v[162:165], v[54:57]
	v_mfma_f32_16x16x32_bf16 v[50:53], v[202:205], v[162:165], v[50:53]
	v_mfma_f32_16x16x32_bf16 v[38:41], v[194:197], v[170:173], v[38:41]
	v_mfma_f32_16x16x32_bf16 v[34:37], v[202:205], v[170:173], v[34:37]
	s_mov_b32 m0, s46
	v_mfma_f32_16x16x32_bf16 v[22:25], v[194:197], v[178:181], v[22:25]
	global_load_lds_dwordx4 v0, s[44:45]
	v_mfma_f32_16x16x32_bf16 v[18:21], v[202:205], v[178:181], v[18:21]
	v_mfma_f32_16x16x32_bf16 v[6:9], v[194:197], v[186:189], v[6:9]
	v_mfma_f32_16x16x32_bf16 v[2:5], v[202:205], v[186:189], v[2:5]
	v_mfma_f32_16x16x32_bf16 v[54:57], v[198:201], v[166:169], v[54:57]
	v_mfma_f32_16x16x32_bf16 v[50:53], v[206:209], v[166:169], v[50:53]
	s_add_i32 m0, s46, 0x2000
	v_mfma_f32_16x16x32_bf16 v[38:41], v[198:201], v[174:177], v[38:41]
	global_load_lds_dwordx4 v130, s[44:45]
	v_mfma_f32_16x16x32_bf16 v[34:37], v[206:209], v[174:177], v[34:37]
	v_mfma_f32_16x16x32_bf16 v[22:25], v[198:201], v[182:185], v[22:25]
	v_mfma_f32_16x16x32_bf16 v[18:21], v[206:209], v[182:185], v[18:21]
	v_mfma_f32_16x16x32_bf16 v[6:9], v[198:201], v[190:193], v[6:9]
	v_mfma_f32_16x16x32_bf16 v[2:5], v[206:209], v[190:193], v[2:5]
	s_add_i32 s44, 0, 0x18000
	v_add_u32_e32 v158, s44, v143
	s_barrier
	ds_read_b128 v[146:149], v158
	ds_read_b128 v[150:153], v158 offset:1024
	ds_read_b128 v[154:157], v158 offset:2048
	ds_read_b128 v[158:161], v158 offset:3072
	s_add_u32 s24, s24, 0x80000
	s_addc_u32 s25, s25, 0
	ds_read_b128 v[162:165], v145 offset:32768
	ds_read_b128 v[166:169], v145 offset:33792
	ds_read_b128 v[170:173], v145 offset:34816
	ds_read_b128 v[174:177], v145 offset:35840
	ds_read_b128 v[178:181], v145 offset:36864
	ds_read_b128 v[182:185], v145 offset:37888
	ds_read_b128 v[186:189], v145 offset:38912
	ds_read_b128 v[190:193], v145 offset:39936
	s_waitcnt lgkmcnt(8)
	s_barrier
	s_waitcnt lgkmcnt(0)
	v_mfma_f32_16x16x32_bf16 v[126:129], v[146:149], v[162:165], v[126:129]
	v_mfma_f32_16x16x32_bf16 v[122:125], v[154:157], v[162:165], v[122:125]
	v_mfma_f32_16x16x32_bf16 v[110:113], v[146:149], v[170:173], v[110:113]
	v_mfma_f32_16x16x32_bf16 v[106:109], v[154:157], v[170:173], v[106:109]
	s_mov_b32 m0, s35
	v_mfma_f32_16x16x32_bf16 v[94:97], v[146:149], v[178:181], v[94:97]
	global_load_lds_dwordx4 v134, s[24:25]
	v_mfma_f32_16x16x32_bf16 v[90:93], v[154:157], v[178:181], v[90:93]
	v_mfma_f32_16x16x32_bf16 v[78:81], v[146:149], v[186:189], v[78:81]
	v_mfma_f32_16x16x32_bf16 v[74:77], v[154:157], v[186:189], v[74:77]
	v_mfma_f32_16x16x32_bf16 v[126:129], v[150:153], v[166:169], v[126:129]
	v_mfma_f32_16x16x32_bf16 v[122:125], v[158:161], v[166:169], v[122:125]
	s_mov_b32 m0, s36
	v_mfma_f32_16x16x32_bf16 v[110:113], v[150:153], v[174:177], v[110:113]
	global_load_lds_dwordx4 v132, s[24:25]
	v_mfma_f32_16x16x32_bf16 v[106:109], v[158:161], v[174:177], v[106:109]
	v_mfma_f32_16x16x32_bf16 v[94:97], v[150:153], v[182:185], v[94:97]
	v_mfma_f32_16x16x32_bf16 v[90:93], v[158:161], v[182:185], v[90:93]
	v_mfma_f32_16x16x32_bf16 v[78:81], v[150:153], v[190:193], v[78:81]
	v_mfma_f32_16x16x32_bf16 v[74:77], v[158:161], v[190:193], v[74:77]
	s_barrier
	s_add_i32 s24, 0, 0x1c000
	s_add_i32 s25, s44, s30
	v_add_u32_e32 v206, s24, v143
	s_add_u32 s44, s22, 0x80
	s_addc_u32 s45, s23, 0
	ds_read_b128 v[194:197], v206
	ds_read_b128 v[198:201], v206 offset:1024
	ds_read_b128 v[202:205], v206 offset:2048
	ds_read_b128 v[206:209], v206 offset:3072
	s_barrier
	s_waitcnt lgkmcnt(0)
	v_mfma_f32_16x16x32_bf16 v[118:121], v[194:197], v[162:165], v[118:121]
	v_mfma_f32_16x16x32_bf16 v[114:117], v[202:205], v[162:165], v[114:117]
	v_mfma_f32_16x16x32_bf16 v[102:105], v[194:197], v[170:173], v[102:105]
	v_mfma_f32_16x16x32_bf16 v[98:101], v[202:205], v[170:173], v[98:101]
	s_mov_b32 m0, s25
	v_mfma_f32_16x16x32_bf16 v[86:89], v[194:197], v[178:181], v[86:89]
	global_load_lds_dwordx4 v0, s[44:45]
	v_mfma_f32_16x16x32_bf16 v[82:85], v[202:205], v[178:181], v[82:85]
	v_mfma_f32_16x16x32_bf16 v[70:73], v[194:197], v[186:189], v[70:73]
	v_mfma_f32_16x16x32_bf16 v[66:69], v[202:205], v[186:189], v[66:69]
	v_mfma_f32_16x16x32_bf16 v[118:121], v[198:201], v[166:169], v[118:121]
	v_mfma_f32_16x16x32_bf16 v[114:117], v[206:209], v[166:169], v[114:117]
	s_add_i32 m0, s25, 0x2000
	v_mfma_f32_16x16x32_bf16 v[102:105], v[198:201], v[174:177], v[102:105]
	global_load_lds_dwordx4 v130, s[44:45]
	v_mfma_f32_16x16x32_bf16 v[98:101], v[206:209], v[174:177], v[98:101]
	v_mfma_f32_16x16x32_bf16 v[86:89], v[198:201], v[182:185], v[86:89]
	v_mfma_f32_16x16x32_bf16 v[82:85], v[206:209], v[182:185], v[82:85]
	v_mfma_f32_16x16x32_bf16 v[70:73], v[198:201], v[190:193], v[70:73]
	v_mfma_f32_16x16x32_bf16 v[66:69], v[206:209], v[190:193], v[66:69]
	s_barrier
	ds_read_b128 v[162:165], v145 offset:49152
	ds_read_b128 v[166:169], v145 offset:50176
	ds_read_b128 v[170:173], v145 offset:51200
	ds_read_b128 v[174:177], v145 offset:52224
	ds_read_b128 v[178:181], v145 offset:53248
	ds_read_b128 v[182:185], v145 offset:54272
	ds_read_b128 v[186:189], v145 offset:55296
	ds_read_b128 v[190:193], v145 offset:56320
	s_barrier
; __device__ __forceinline__ unsigned cvt_pk_bf16(float lo, float hi) { f32x2_t v = {lo, hi}; bf16x2_t b = __builtin_convertvector(v, bf16x2_t); return __builtin_bit_cast(unsigned, b); }
; #define PG8_STAGE(bufoff, gbase, voff) do { _Pragma("unroll") for (int _i = 0; _i < 2; ++_i) \
;         __builtin_amdgcn_global_load_lds((const unsigned*)((const char*)(gbase) + (voff)[_i]), (LAS unsigned*)(lds + (bufoff) + ldsw + _i * 8192), 16, 0, 0); } while (0)
; #define PG8_LDA(dst, b, h) do { _Pragma("unroll") for (int m = 0; m < 4; ++m) _Pragma("unroll") for (int k = 0; k < 2; ++k) dst[m][k] = *(const LAS bf16x8*)(lds + PG8_SA(b, h) + aoff + m * 2048 + k * 1024); } while (0)
; template <class Epi, class Sched>
; __device__ __forceinline__ void gemm_phase(LAS unsigned char* lds, const Gemm g, const Sched& S, const Epi& E) {
;     ...
;             PG8_BAR; PG8_WAIT_L(0); PG8_MMA(0, 1, At, B1); PG8_BAR;
;             PG8_LDA(At, 1, 1); PG8_STAGE(PG8_SA(1, 0), a3, voffA);
;             PG8_BAR; PG8_WAIT_L(0); PG8_MMA(1, 0, At, B0); PG8_BAR; PG8_SCHED;
;             PG8_STAGE(PG8_SB(1, 1), b3 + hstep, voffB);
;             PG8_WAIT_V(6); PG8_BAR; PG8_MMA(1, 1, At, B1); PG8_BAR;
;     __device__ __forceinline__ void operator()(const f32x4 (&acc)[2][2][4][2], const pg8::Unit& u, int wr, int wc, int fr, int fq) const {
;         const int row0 = u.pm * 256 + wr * 64 + fr; const int col0 = u.pn * 256 + wc * 32 + 8 * fq;
; #pragma unroll
;         for (int ai = 0; ai < 2; ++ai)
; #pragma unroll
;             for (int m = 0; m < 4; ++m) { const int row = row0 + ai * 128 + m * 16; bf16_t* rowp = O + (size_t)row * ldc + col0;
; #pragma unroll
;                 for (int bj = 0; bj < 2; ++bj) { f32x4 v0 = acc[ai][bj][m][0], v1 = acc[ai][bj][m][1];
;                     if (ACT == 1) {
; #pragma unroll
;                         for (int j = 0; j < 4; ++j) { float a = fmaxf(v0[j], 0.f), b = fmaxf(v1[j], 0.f); v0[j] = a * a; v1[j] = b * b; } }
;                     if (ACT == 0) { if (u.pn == (C_G / 256) && bj == 0 && wc == 0 && fq < 2) { float* gp = gate + (size_t)row * 16 + 8 * fq; *(f32x4*)gp = v0; *(f32x4*)(gp + 4) = v1; } }
;                     u32x4 w; w.x = cvt_pk_bf16(v0[0], v0[1]); w.y = cvt_pk_bf16(v0[2], v0[3]); w.z = cvt_pk_bf16(v1[0], v1[1]); w.w = cvt_pk_bf16(v1[2], v1[3]);
;                     *(u32x4*)(rowp + bj * 128) = w; } }
	s_waitcnt lgkmcnt(0)
	v_mfma_f32_16x16x32_bf16 v[62:65], v[146:149], v[162:165], v[62:65]
	v_mfma_f32_16x16x32_bf16 v[58:61], v[154:157], v[162:165], v[58:61]
	v_mfma_f32_16x16x32_bf16 v[46:49], v[146:149], v[170:173], v[46:49]
	v_mfma_f32_16x16x32_bf16 v[42:45], v[154:157], v[170:173], v[42:45]
	s_mov_b32 m0, s37
	v_mfma_f32_16x16x32_bf16 v[30:33], v[146:149], v[178:181], v[30:33]
	global_load_lds_dwordx4 v134, s[48:49]
	v_mfma_f32_16x16x32_bf16 v[26:29], v[154:157], v[178:181], v[26:29]
	v_mfma_f32_16x16x32_bf16 v[14:17], v[146:149], v[186:189], v[14:17]
	v_mfma_f32_16x16x32_bf16 v[10:13], v[154:157], v[186:189], v[10:13]
	v_mfma_f32_16x16x32_bf16 v[62:65], v[150:153], v[166:169], v[62:65]
	v_mfma_f32_16x16x32_bf16 v[58:61], v[158:161], v[166:169], v[58:61]
	s_mov_b32 m0, s38
	v_mfma_f32_16x16x32_bf16 v[46:49], v[150:153], v[174:177], v[46:49]
	global_load_lds_dwordx4 v132, s[48:49]
	v_mfma_f32_16x16x32_bf16 v[42:45], v[158:161], v[174:177], v[42:45]
	v_mfma_f32_16x16x32_bf16 v[30:33], v[150:153], v[182:185], v[30:33]
	v_mfma_f32_16x16x32_bf16 v[26:29], v[158:161], v[182:185], v[26:29]
	v_mfma_f32_16x16x32_bf16 v[14:17], v[150:153], v[190:193], v[14:17]
	v_mfma_f32_16x16x32_bf16 v[10:13], v[158:161], v[190:193], v[10:13]
	s_barrier
	s_add_u32 s22, s22, 0x80080
	s_addc_u32 s23, s23, 0
	s_add_i32 s24, s24, s30
	s_waitcnt vmcnt(4)
	s_barrier
	v_mfma_f32_16x16x32_bf16 v[54:57], v[194:197], v[162:165], v[54:57]
	v_mfma_f32_16x16x32_bf16 v[50:53], v[202:205], v[162:165], v[50:53]
	v_mfma_f32_16x16x32_bf16 v[38:41], v[194:197], v[170:173], v[38:41]
	v_mfma_f32_16x16x32_bf16 v[34:37], v[202:205], v[170:173], v[34:37]
	s_mov_b32 m0, s24
	v_mfma_f32_16x16x32_bf16 v[22:25], v[194:197], v[178:181], v[22:25]
	global_load_lds_dwordx4 v0, s[22:23]
	v_mfma_f32_16x16x32_bf16 v[18:21], v[202:205], v[178:181], v[18:21]
	v_mfma_f32_16x16x32_bf16 v[6:9], v[194:197], v[186:189], v[6:9]
	v_mfma_f32_16x16x32_bf16 v[2:5], v[202:205], v[186:189], v[2:5]
	v_mfma_f32_16x16x32_bf16 v[54:57], v[198:201], v[166:169], v[54:57]
	v_mfma_f32_16x16x32_bf16 v[50:53], v[206:209], v[166:169], v[50:53]
	s_add_i32 m0, s24, 0x2000
	v_mfma_f32_16x16x32_bf16 v[38:41], v[198:201], v[174:177], v[38:41]
	global_load_lds_dwordx4 v130, s[22:23]
	v_mfma_f32_16x16x32_bf16 v[34:37], v[206:209], v[174:177], v[34:37]
	v_mfma_f32_16x16x32_bf16 v[22:25], v[198:201], v[182:185], v[22:25]
	v_mfma_f32_16x16x32_bf16 v[18:21], v[206:209], v[182:185], v[18:21]
	v_mfma_f32_16x16x32_bf16 v[6:9], v[198:201], v[190:193], v[6:9]
	v_mfma_f32_16x16x32_bf16 v[2:5], v[206:209], v[190:193], v[2:5]
	s_add_i32 s43, s43, 2
	s_add_u32 s20, s20, 0x100
	s_addc_u32 s21, s21, 0
	s_add_u32 s41, s41, 0x100
	s_addc_u32 s42, s42, 0
	s_cmp_gt_u32 s43, 29
	s_barrier
	s_cbranch_scc0 .LBB0_1279
	v_lshl_add_u32 v146, s18, 8, v142
	v_lshl_or_b32 v140, s16, 8, v144
	v_ashrrev_i32_e32 v147, 31, v146
	v_ashrrev_i32_e32 v141, 31, v140
	v_lshlrev_b64 v[148:149], 14, v[146:147]
	v_max_f32_e32 v122, v122, v122
	v_max_f32_e32 v123, v123, v123
	v_lshl_add_u64 v[148:149], s[58:59], 0, v[148:149]
	v_lshlrev_b64 v[150:151], 1, v[140:141]
	v_max_f32_e32 v122, 0, v122
	v_max_f32_e32 v123, 0, v123
	v_lshl_add_u64 v[140:141], v[148:149], 0, v[150:151]
	v_pk_mul_f32 v[148:149], v[122:123], v[122:123]
	v_max_f32_e32 v123, v124, v124
	v_max_f32_e32 v126, v126, v126
	v_max_f32_e32 v127, v127, v127
	v_max_f32_e32 v122, v128, v128
	v_max_f32_e32 v124, 0, v123
	v_max_f32_e32 v123, v129, v129
	v_max_f32_e32 v125, v125, v125
	v_max_f32_e32 v126, 0, v126
	v_max_f32_e32 v127, 0, v127
	v_max_f32_e32 v122, 0, v122
	v_max_f32_e32 v123, 0, v123
	v_max_f32_e32 v125, 0, v125
	v_pk_mul_f32 v[126:127], v[126:127], v[126:127]
	v_pk_mul_f32 v[128:129], v[122:123], v[122:123]
	v_pk_mul_f32 v[152:153], v[124:125], v[124:125]
	v_max_f32_e32 v114, v114, v114
	v_max_f32_e32 v115, v115, v115
	v_cvt_pk_bf16_f32 v122, v126, v127
	v_cvt_pk_bf16_f32 v123, v128, v129
	v_cvt_pk_bf16_f32 v124, v148, v149
	v_cvt_pk_bf16_f32 v125, v152, v153
	v_max_f32_e32 v114, 0, v114
	v_max_f32_e32 v115, 0, v115
	global_store_dwordx4 v[140:141], v[122:125], off
	v_max_f32_e32 v118, v118, v118
	v_max_f32_e32 v119, v119, v119
	v_pk_mul_f32 v[122:123], v[114:115], v[114:115]
	v_max_f32_e32 v115, v116, v116
	v_max_f32_e32 v114, v120, v120
	v_max_f32_e32 v116, 0, v115
	v_max_f32_e32 v115, v121, v121
	v_max_f32_e32 v117, v117, v117
	v_max_f32_e32 v118, 0, v118
	v_max_f32_e32 v119, 0, v119
	v_max_f32_e32 v114, 0, v114
	v_max_f32_e32 v115, 0, v115
	v_max_f32_e32 v117, 0, v117
	v_pk_mul_f32 v[118:119], v[118:119], v[118:119]
	v_pk_mul_f32 v[120:121], v[114:115], v[114:115]
	v_pk_mul_f32 v[124:125], v[116:117], v[116:117]
	v_max_f32_e32 v106, v106, v106
	v_max_f32_e32 v107, v107, v107
	v_cvt_pk_bf16_f32 v114, v118, v119
	v_cvt_pk_bf16_f32 v115, v120, v121
	v_cvt_pk_bf16_f32 v116, v122, v123
	v_cvt_pk_bf16_f32 v117, v124, v125
	v_max_f32_e32 v106, 0, v106
	v_max_f32_e32 v107, 0, v107
	global_store_dwordx4 v[140:141], v[114:117], off offset:256
	v_max_f32_e32 v110, v110, v110
	v_max_f32_e32 v111, v111, v111
	v_or_b32_e32 v114, 16, v146
	v_pk_mul_f32 v[116:117], v[106:107], v[106:107]
	v_max_f32_e32 v107, v108, v108
	v_ashrrev_i32_e32 v115, 31, v114
	v_max_f32_e32 v106, v112, v112
	v_max_f32_e32 v108, 0, v107
	v_max_f32_e32 v107, v113, v113
	v_max_f32_e32 v109, v109, v109
	v_lshlrev_b64 v[114:115], 14, v[114:115]
	v_max_f32_e32 v110, 0, v110
	v_max_f32_e32 v111, 0, v111
	v_max_f32_e32 v106, 0, v106
	v_max_f32_e32 v107, 0, v107
	v_max_f32_e32 v109, 0, v109
	v_lshl_add_u64 v[114:115], s[58:59], 0, v[114:115]
	v_pk_mul_f32 v[110:111], v[110:111], v[110:111]
	v_pk_mul_f32 v[112:113], v[106:107], v[106:107]
; __device__ __forceinline__ unsigned cvt_pk_bf16(float lo, float hi) { f32x2_t v = {lo, hi}; bf16x2_t b = __builtin_convertvector(v, bf16x2_t); return __builtin_bit_cast(unsigned, b); }
;     __device__ __forceinline__ void operator()(const f32x4 (&acc)[2][2][4][2], const pg8::Unit& u, int wr, int wc, int fr, int fq) const {
;     ...
;             for (int m = 0; m < 4; ++m) { const int row = row0 + ai * 128 + m * 16; bf16_t* rowp = O + (size_t)row * ldc + col0;
; #pragma unroll
;                 for (int bj = 0; bj < 2; ++bj) { f32x4 v0 = acc[ai][bj][m][0], v1 = acc[ai][bj][m][1];
;                     if (ACT == 1) {
; #pragma unroll
;                         for (int j = 0; j < 4; ++j) { float a = fmaxf(v0[j], 0.f), b = fmaxf(v1[j], 0.f); v0[j] = a * a; v1[j] = b * b; } }
;                     if (ACT == 0) { if (u.pn == (C_G / 256) && bj == 0 && wc == 0 && fq < 2) { float* gp = gate + (size_t)row * 16 + 8 * fq; *(f32x4*)gp = v0; *(f32x4*)(gp + 4) = v1; } }
;                     u32x4 w; w.x = cvt_pk_bf16(v0[0], v0[1]); w.y = cvt_pk_bf16(v0[2], v0[3]); w.z = cvt_pk_bf16(v1[0], v1[1]); w.w = cvt_pk_bf16(v1[2], v1[3]);
;                     *(u32x4*)(rowp + bj * 128) = w; } }
	v_pk_mul_f32 v[118:119], v[108:109], v[108:109]
	v_max_f32_e32 v98, v98, v98
	v_max_f32_e32 v99, v99, v99
	v_lshl_add_u64 v[114:115], v[114:115], 0, v[150:151]
	v_cvt_pk_bf16_f32 v106, v110, v111
	v_cvt_pk_bf16_f32 v107, v112, v113
	v_cvt_pk_bf16_f32 v108, v116, v117
	v_cvt_pk_bf16_f32 v109, v118, v119
	v_max_f32_e32 v98, 0, v98
	v_max_f32_e32 v99, 0, v99
	global_store_dwordx4 v[114:115], v[106:109], off
	v_max_f32_e32 v102, v102, v102
	v_max_f32_e32 v103, v103, v103
	v_pk_mul_f32 v[106:107], v[98:99], v[98:99]
	v_max_f32_e32 v99, v100, v100
	v_max_f32_e32 v98, v104, v104
	v_max_f32_e32 v100, 0, v99
	v_max_f32_e32 v99, v105, v105
	v_max_f32_e32 v101, v101, v101
	v_max_f32_e32 v102, 0, v102
	v_max_f32_e32 v103, 0, v103
	v_max_f32_e32 v98, 0, v98
	v_max_f32_e32 v99, 0, v99
	v_max_f32_e32 v101, 0, v101
	v_pk_mul_f32 v[102:103], v[102:103], v[102:103]
	v_pk_mul_f32 v[104:105], v[98:99], v[98:99]
	v_pk_mul_f32 v[108:109], v[100:101], v[100:101]
	v_max_f32_e32 v90, v90, v90
	v_max_f32_e32 v91, v91, v91
	v_cvt_pk_bf16_f32 v98, v102, v103
	v_cvt_pk_bf16_f32 v99, v104, v105
	v_cvt_pk_bf16_f32 v100, v106, v107
	v_cvt_pk_bf16_f32 v101, v108, v109
	v_max_f32_e32 v90, 0, v90
	v_max_f32_e32 v91, 0, v91
	global_store_dwordx4 v[114:115], v[98:101], off offset:256
	v_max_f32_e32 v94, v94, v94
	v_max_f32_e32 v95, v95, v95
	v_or_b32_e32 v98, 32, v146
	v_pk_mul_f32 v[100:101], v[90:91], v[90:91]
	v_max_f32_e32 v91, v92, v92
	v_ashrrev_i32_e32 v99, 31, v98
	v_max_f32_e32 v90, v96, v96
	v_max_f32_e32 v92, 0, v91
	v_max_f32_e32 v91, v97, v97
	v_max_f32_e32 v93, v93, v93
	v_lshlrev_b64 v[98:99], 14, v[98:99]
	v_max_f32_e32 v94, 0, v94
	v_max_f32_e32 v95, 0, v95
	v_max_f32_e32 v90, 0, v90
	v_max_f32_e32 v91, 0, v91
	v_max_f32_e32 v93, 0, v93
	v_lshl_add_u64 v[98:99], s[58:59], 0, v[98:99]
	v_pk_mul_f32 v[94:95], v[94:95], v[94:95]
	v_pk_mul_f32 v[96:97], v[90:91], v[90:91]
	v_pk_mul_f32 v[102:103], v[92:93], v[92:93]
	v_max_f32_e32 v82, v82, v82
	v_max_f32_e32 v83, v83, v83
	v_lshl_add_u64 v[98:99], v[98:99], 0, v[150:151]
	v_cvt_pk_bf16_f32 v90, v94, v95
	v_cvt_pk_bf16_f32 v91, v96, v97
	v_cvt_pk_bf16_f32 v92, v100, v101
	v_cvt_pk_bf16_f32 v93, v102, v103
	v_max_f32_e32 v82, 0, v82
	v_max_f32_e32 v83, 0, v83
	global_store_dwordx4 v[98:99], v[90:93], off
	v_max_f32_e32 v86, v86, v86
	v_max_f32_e32 v87, v87, v87
	v_pk_mul_f32 v[90:91], v[82:83], v[82:83]
	v_max_f32_e32 v83, v84, v84
	v_max_f32_e32 v82, v88, v88
	v_max_f32_e32 v84, 0, v83
	v_max_f32_e32 v83, v89, v89
	v_max_f32_e32 v85, v85, v85
	v_max_f32_e32 v86, 0, v86
	v_max_f32_e32 v87, 0, v87
	v_max_f32_e32 v82, 0, v82
	v_max_f32_e32 v83, 0, v83
	v_max_f32_e32 v85, 0, v85
	v_pk_mul_f32 v[86:87], v[86:87], v[86:87]
	v_pk_mul_f32 v[88:89], v[82:83], v[82:83]
	v_pk_mul_f32 v[92:93], v[84:85], v[84:85]
	v_max_f32_e32 v74, v74, v74
	v_max_f32_e32 v75, v75, v75
	v_cvt_pk_bf16_f32 v82, v86, v87
	v_cvt_pk_bf16_f32 v83, v88, v89
	v_cvt_pk_bf16_f32 v84, v90, v91
	v_cvt_pk_bf16_f32 v85, v92, v93
	v_max_f32_e32 v74, 0, v74
	v_max_f32_e32 v75, 0, v75
	global_store_dwordx4 v[98:99], v[82:85], off offset:256
	v_max_f32_e32 v78, v78, v78
	v_max_f32_e32 v79, v79, v79
	v_or_b32_e32 v82, 48, v146
	v_pk_mul_f32 v[84:85], v[74:75], v[74:75]
	v_max_f32_e32 v75, v76, v76
	v_ashrrev_i32_e32 v83, 31, v82
	v_max_f32_e32 v74, v80, v80
	v_max_f32_e32 v76, 0, v75
	v_max_f32_e32 v75, v81, v81
	v_max_f32_e32 v77, v77, v77
	v_lshlrev_b64 v[82:83], 14, v[82:83]
	v_max_f32_e32 v78, 0, v78
	v_max_f32_e32 v79, 0, v79
	v_max_f32_e32 v74, 0, v74
	v_max_f32_e32 v75, 0, v75
	v_max_f32_e32 v77, 0, v77
	v_lshl_add_u64 v[82:83], s[58:59], 0, v[82:83]
	v_pk_mul_f32 v[78:79], v[78:79], v[78:79]
	v_pk_mul_f32 v[80:81], v[74:75], v[74:75]
	v_pk_mul_f32 v[86:87], v[76:77], v[76:77]
	v_max_f32_e32 v66, v66, v66
	v_max_f32_e32 v67, v67, v67
	v_lshl_add_u64 v[82:83], v[82:83], 0, v[150:151]
	v_cvt_pk_bf16_f32 v74, v78, v79
	v_cvt_pk_bf16_f32 v75, v80, v81
	v_cvt_pk_bf16_f32 v76, v84, v85
	v_cvt_pk_bf16_f32 v77, v86, v87
	v_max_f32_e32 v66, 0, v66
	v_max_f32_e32 v67, 0, v67
	global_store_dwordx4 v[82:83], v[74:77], off
	v_max_f32_e32 v70, v70, v70
	v_max_f32_e32 v71, v71, v71
	v_pk_mul_f32 v[74:75], v[66:67], v[66:67]
	v_max_f32_e32 v67, v68, v68
	v_max_f32_e32 v66, v72, v72
	v_max_f32_e32 v68, 0, v67
	v_max_f32_e32 v67, v73, v73
	v_max_f32_e32 v69, v69, v69
	v_max_f32_e32 v70, 0, v70
	v_max_f32_e32 v71, 0, v71
	v_max_f32_e32 v66, 0, v66
	v_max_f32_e32 v67, 0, v67
	v_max_f32_e32 v69, 0, v69
	v_pk_mul_f32 v[70:71], v[70:71], v[70:71]
	v_pk_mul_f32 v[72:73], v[66:67], v[66:67]
	v_pk_mul_f32 v[76:77], v[68:69], v[68:69]
	v_max_f32_e32 v58, v58, v58
	v_max_f32_e32 v59, v59, v59
	v_cvt_pk_bf16_f32 v66, v70, v71
	v_cvt_pk_bf16_f32 v67, v72, v73
	v_cvt_pk_bf16_f32 v68, v74, v75
	v_cvt_pk_bf16_f32 v69, v76, v77
	v_max_f32_e32 v58, 0, v58
	v_max_f32_e32 v59, 0, v59
	global_store_dwordx4 v[82:83], v[66:69], off offset:256
	v_max_f32_e32 v62, v62, v62
	v_max_f32_e32 v63, v63, v63
	v_pk_mul_f32 v[68:69], v[58:59], v[58:59]
	v_max_f32_e32 v59, v60, v60
	v_max_f32_e32 v62, 0, v62
	v_max_f32_e32 v63, 0, v63
	v_max_f32_e32 v58, v64, v64
	v_max_f32_e32 v60, 0, v59
	v_max_f32_e32 v59, v65, v65
	v_max_f32_e32 v61, v61, v61
	v_pk_mul_f32 v[62:63], v[62:63], v[62:63]
	v_max_f32_e32 v58, 0, v58
	v_max_f32_e32 v59, 0, v59
	v_max_f32_e32 v61, 0, v61
	s_mov_b32 s3, 0x200000
	v_pk_mul_f32 v[64:65], v[58:59], v[58:59]
	v_pk_mul_f32 v[70:71], v[60:61], v[60:61]
	v_cvt_pk_bf16_f32 v58, v62, v63
	v_add_co_u32_e32 v62, vcc, s3, v140
	v_max_f32_e32 v50, v50, v50
	v_max_f32_e32 v51, v51, v51
	v_cvt_pk_bf16_f32 v59, v64, v65
	v_cvt_pk_bf16_f32 v60, v68, v69
	v_cvt_pk_bf16_f32 v61, v70, v71
; __device__ __forceinline__ unsigned cvt_pk_bf16(float lo, float hi) { f32x2_t v = {lo, hi}; bf16x2_t b = __builtin_convertvector(v, bf16x2_t); return __builtin_bit_cast(unsigned, b); }
; #define PG8_WAIT_V(n) asm volatile("s_waitcnt vmcnt(" #n ")" ::: "memory")
; #define PG8_BAR __builtin_amdgcn_s_barrier()
; template <class Epi, class Sched>
; __device__ __forceinline__ void gemm_phase(LAS unsigned char* lds, const Gemm g, const Sched& S, const Epi& E) {
;     ...
;         if (!has_next) break;
; #pragma unroll
;         for (int a = 0; a < 2; ++a)
; #pragma unroll
;             for (int b = 0; b < 2; ++b)
; #pragma unroll
;                 for (int m = 0; m < 4; ++m)
; #pragma unroll
;                     for (int n = 0; n < 2; ++n) acc[a][b][m][n] = (f32x4){0.f, 0.f, 0.f, 0.f};
;         cur = nxt; cA = nA; cB = nB; ++ui;
;     }
;     PG8_WAIT_V(0);
;     if (wr == 0) PG8_BAR;
;     PG8_BAR;
;     __device__ __forceinline__ void operator()(const f32x4 (&acc)[2][2][4][2], const pg8::Unit& u, int wr, int wc, int fr, int fq) const {
;     ...
;             for (int m = 0; m < 4; ++m) { const int row = row0 + ai * 128 + m * 16; bf16_t* rowp = O + (size_t)row * ldc + col0;
; #pragma unroll
;                 for (int bj = 0; bj < 2; ++bj) { f32x4 v0 = acc[ai][bj][m][0], v1 = acc[ai][bj][m][1];
;                     if (ACT == 1) {
; #pragma unroll
;                         for (int j = 0; j < 4; ++j) { float a = fmaxf(v0[j], 0.f), b = fmaxf(v1[j], 0.f); v0[j] = a * a; v1[j] = b * b; } }
;                     if (ACT == 0) { if (u.pn == (C_G / 256) && bj == 0 && wc == 0 && fq < 2) { float* gp = gate + (size_t)row * 16 + 8 * fq; *(f32x4*)gp = v0; *(f32x4*)(gp + 4) = v1; } }
;                     u32x4 w; w.x = cvt_pk_bf16(v0[0], v0[1]); w.y = cvt_pk_bf16(v0[2], v0[3]); w.z = cvt_pk_bf16(v1[0], v1[1]); w.w = cvt_pk_bf16(v1[2], v1[3]);
;                     *(u32x4*)(rowp + bj * 128) = w; } }
	v_addc_co_u32_e32 v63, vcc, 0, v141, vcc
	v_max_f32_e32 v50, 0, v50
	v_max_f32_e32 v51, 0, v51
	global_store_dwordx4 v[62:63], v[58:61], off
	v_max_f32_e32 v54, v54, v54
	v_max_f32_e32 v55, v55, v55
	v_pk_mul_f32 v[58:59], v[50:51], v[50:51]
	v_max_f32_e32 v51, v52, v52
	v_max_f32_e32 v50, v56, v56
	v_max_f32_e32 v52, 0, v51
	v_max_f32_e32 v51, v57, v57
	v_max_f32_e32 v53, v53, v53
	v_max_f32_e32 v54, 0, v54
	v_max_f32_e32 v55, 0, v55
	v_max_f32_e32 v50, 0, v50
	v_max_f32_e32 v51, 0, v51
	v_max_f32_e32 v53, 0, v53
	s_mov_b64 s[20:21], 0x200000
	v_pk_mul_f32 v[54:55], v[54:55], v[54:55]
	v_pk_mul_f32 v[56:57], v[50:51], v[50:51]
	v_pk_mul_f32 v[60:61], v[52:53], v[52:53]
	v_max_f32_e32 v42, v42, v42
	v_max_f32_e32 v43, v43, v43
	v_lshl_add_u64 v[66:67], v[140:141], 0, s[20:21]
	v_cvt_pk_bf16_f32 v50, v54, v55
	v_cvt_pk_bf16_f32 v51, v56, v57
	v_cvt_pk_bf16_f32 v52, v58, v59
	v_cvt_pk_bf16_f32 v53, v60, v61
	v_max_f32_e32 v42, 0, v42
	v_max_f32_e32 v43, 0, v43
	global_store_dwordx4 v[66:67], v[50:53], off offset:256
	v_max_f32_e32 v46, v46, v46
	v_max_f32_e32 v47, v47, v47
	v_pk_mul_f32 v[52:53], v[42:43], v[42:43]
	v_max_f32_e32 v43, v44, v44
	v_max_f32_e32 v46, 0, v46
	v_max_f32_e32 v47, 0, v47
	v_max_f32_e32 v42, v48, v48
	v_max_f32_e32 v44, 0, v43
	v_max_f32_e32 v43, v49, v49
	v_max_f32_e32 v45, v45, v45
	v_pk_mul_f32 v[46:47], v[46:47], v[46:47]
	v_max_f32_e32 v42, 0, v42
	v_max_f32_e32 v43, 0, v43
	v_max_f32_e32 v45, 0, v45
	s_mov_b32 s3, 0x240000
	v_pk_mul_f32 v[48:49], v[42:43], v[42:43]
	v_pk_mul_f32 v[54:55], v[44:45], v[44:45]
	v_cvt_pk_bf16_f32 v42, v46, v47
	v_add_co_u32_e32 v46, vcc, s3, v140
	v_max_f32_e32 v34, v34, v34
	v_max_f32_e32 v35, v35, v35
	v_cvt_pk_bf16_f32 v43, v48, v49
	v_cvt_pk_bf16_f32 v44, v52, v53
	v_cvt_pk_bf16_f32 v45, v54, v55
	v_addc_co_u32_e32 v47, vcc, 0, v141, vcc
	v_max_f32_e32 v34, 0, v34
	v_max_f32_e32 v35, 0, v35
	global_store_dwordx4 v[46:47], v[42:45], off
	v_max_f32_e32 v38, v38, v38
	v_max_f32_e32 v39, v39, v39
	v_pk_mul_f32 v[42:43], v[34:35], v[34:35]
	v_max_f32_e32 v35, v36, v36
	v_max_f32_e32 v34, v40, v40
	v_max_f32_e32 v36, 0, v35
	v_max_f32_e32 v35, v41, v41
	v_max_f32_e32 v37, v37, v37
	v_max_f32_e32 v38, 0, v38
	v_max_f32_e32 v39, 0, v39
	v_max_f32_e32 v34, 0, v34
	v_max_f32_e32 v35, 0, v35
	v_max_f32_e32 v37, 0, v37
	s_mov_b64 s[20:21], 0x240000
	v_pk_mul_f32 v[38:39], v[38:39], v[38:39]
	v_pk_mul_f32 v[40:41], v[34:35], v[34:35]
	v_pk_mul_f32 v[44:45], v[36:37], v[36:37]
	v_max_f32_e32 v26, v26, v26
	v_max_f32_e32 v27, v27, v27
	v_lshl_add_u64 v[50:51], v[140:141], 0, s[20:21]
	v_cvt_pk_bf16_f32 v34, v38, v39
	v_cvt_pk_bf16_f32 v35, v40, v41
	v_cvt_pk_bf16_f32 v36, v42, v43
	v_cvt_pk_bf16_f32 v37, v44, v45
	v_max_f32_e32 v26, 0, v26
	v_max_f32_e32 v27, 0, v27
	global_store_dwordx4 v[50:51], v[34:37], off offset:256
	v_max_f32_e32 v30, v30, v30
	v_max_f32_e32 v31, v31, v31
	v_pk_mul_f32 v[36:37], v[26:27], v[26:27]
	v_max_f32_e32 v27, v28, v28
	v_max_f32_e32 v30, 0, v30
	v_max_f32_e32 v31, 0, v31
	v_max_f32_e32 v26, v32, v32
	v_max_f32_e32 v28, 0, v27
	v_max_f32_e32 v27, v33, v33
	v_max_f32_e32 v29, v29, v29
	v_pk_mul_f32 v[30:31], v[30:31], v[30:31]
	v_max_f32_e32 v26, 0, v26
	v_max_f32_e32 v27, 0, v27
	v_max_f32_e32 v29, 0, v29
	s_mov_b32 s3, 0x280000
	v_pk_mul_f32 v[32:33], v[26:27], v[26:27]
	v_pk_mul_f32 v[38:39], v[28:29], v[28:29]
	v_cvt_pk_bf16_f32 v26, v30, v31
	v_add_co_u32_e32 v30, vcc, s3, v140
	v_max_f32_e32 v18, v18, v18
	v_max_f32_e32 v19, v19, v19
	v_cvt_pk_bf16_f32 v27, v32, v33
	v_cvt_pk_bf16_f32 v28, v36, v37
	v_cvt_pk_bf16_f32 v29, v38, v39
	v_addc_co_u32_e32 v31, vcc, 0, v141, vcc
	v_max_f32_e32 v18, 0, v18
	v_max_f32_e32 v19, 0, v19
	global_store_dwordx4 v[30:31], v[26:29], off
	v_max_f32_e32 v22, v22, v22
	v_max_f32_e32 v23, v23, v23
	v_pk_mul_f32 v[26:27], v[18:19], v[18:19]
	v_max_f32_e32 v19, v20, v20
	v_max_f32_e32 v18, v24, v24
	v_max_f32_e32 v20, 0, v19
	v_max_f32_e32 v19, v25, v25
	v_max_f32_e32 v21, v21, v21
	v_max_f32_e32 v22, 0, v22
	v_max_f32_e32 v23, 0, v23
	v_max_f32_e32 v18, 0, v18
	v_max_f32_e32 v19, 0, v19
	v_max_f32_e32 v21, 0, v21
	s_mov_b64 s[20:21], 0x280000
	v_pk_mul_f32 v[22:23], v[22:23], v[22:23]
	v_pk_mul_f32 v[24:25], v[18:19], v[18:19]
	v_pk_mul_f32 v[28:29], v[20:21], v[20:21]
	v_max_f32_e32 v10, v10, v10
	v_max_f32_e32 v11, v11, v11
	v_lshl_add_u64 v[34:35], v[140:141], 0, s[20:21]
	v_cvt_pk_bf16_f32 v18, v22, v23
	v_cvt_pk_bf16_f32 v19, v24, v25
	v_cvt_pk_bf16_f32 v20, v26, v27
	v_cvt_pk_bf16_f32 v21, v28, v29
	v_max_f32_e32 v10, 0, v10
	v_max_f32_e32 v11, 0, v11
	global_store_dwordx4 v[34:35], v[18:21], off offset:256
	v_max_f32_e32 v14, v14, v14
	v_max_f32_e32 v15, v15, v15
	v_pk_mul_f32 v[20:21], v[10:11], v[10:11]
	v_max_f32_e32 v11, v12, v12
	v_max_f32_e32 v14, 0, v14
	v_max_f32_e32 v15, 0, v15
	v_max_f32_e32 v10, v16, v16
	v_max_f32_e32 v12, 0, v11
	v_max_f32_e32 v11, v17, v17
	v_max_f32_e32 v13, v13, v13
	v_pk_mul_f32 v[14:15], v[14:15], v[14:15]
	v_max_f32_e32 v10, 0, v10
	v_max_f32_e32 v11, 0, v11
	v_max_f32_e32 v13, 0, v13
	s_mov_b32 s3, 0x2c0000
	v_pk_mul_f32 v[16:17], v[10:11], v[10:11]
	v_pk_mul_f32 v[22:23], v[12:13], v[12:13]
	v_cvt_pk_bf16_f32 v10, v14, v15
	v_add_co_u32_e32 v14, vcc, s3, v140
	v_max_f32_e32 v2, v2, v2
	v_max_f32_e32 v3, v3, v3
	v_cvt_pk_bf16_f32 v11, v16, v17
	v_cvt_pk_bf16_f32 v12, v20, v21
	v_cvt_pk_bf16_f32 v13, v22, v23
	v_addc_co_u32_e32 v15, vcc, 0, v141, vcc
	v_max_f32_e32 v2, 0, v2
	v_max_f32_e32 v3, 0, v3
	global_store_dwordx4 v[14:15], v[10:13], off
	v_max_f32_e32 v6, v6, v6
	v_max_f32_e32 v7, v7, v7
	v_pk_mul_f32 v[10:11], v[2:3], v[2:3]
	v_max_f32_e32 v3, v4, v4
	v_max_f32_e32 v2, v8, v8
	v_max_f32_e32 v4, 0, v3
	v_max_f32_e32 v3, v9, v9
	v_max_f32_e32 v5, v5, v5
	v_max_f32_e32 v6, 0, v6
	v_max_f32_e32 v7, 0, v7
	v_max_f32_e32 v2, 0, v2
	v_max_f32_e32 v3, 0, v3
	v_max_f32_e32 v5, 0, v5
	s_mov_b64 s[20:21], 0x2c0000
	v_pk_mul_f32 v[6:7], v[6:7], v[6:7]
	v_pk_mul_f32 v[8:9], v[2:3], v[2:3]
	v_pk_mul_f32 v[12:13], v[4:5], v[4:5]
	v_lshl_add_u64 v[18:19], v[140:141], 0, s[20:21]
	v_cvt_pk_bf16_f32 v2, v6, v7
	v_cvt_pk_bf16_f32 v3, v8, v9
	v_cvt_pk_bf16_f32 v4, v10, v11
	v_cvt_pk_bf16_f32 v5, v12, v13
	s_and_b64 vcc, exec, s[0:1]
	s_mov_b32 s16, s8
	s_mov_b32 s18, s10
	s_mov_b64 s[22:23], s[14:15]
	s_mov_b64 s[20:21], s[12:13]
	global_store_dwordx4 v[18:19], v[2:5], off offset:256
	s_cbranch_vccz .LBB0_1276
	s_waitcnt vmcnt(0)
	s_cmpk_gt_u32 s27, 0xff
	s_cbranch_scc1 .LBB0_1283
	s_barrier
